# exact-split emit of the selection: 64-lane prefix sum of the per-lane counts by DPP (row_shr steps + row_bcast) instead of six ds_bpermute round trips through LDS
# baseline (speedup 1.0000x reference)
; __device__ __forceinline__ void select_group(unsigned char* ws, int r0, const bf16_t* __restrict__ kib, int n, float* sc, SelPre& pre, int nr0, const bf16_t* __restrict__ nkib, int nn) {
;     ...
;       int myc = 0;
; #pragma unroll
;       for (int i = 0; i < 64; ++i) myc += (x[i] >= tau2) ? 1 : 0;
;       int incl = myc;
; #pragma unroll
;       for (int d = 1; d < 64; d <<= 1) {
;         const int t = __shfl_up(incl, d);
;         incl += (lane >= d) ? t : 0;
;       }
;       int pos = incl - myc;
.LBB0_3246:
	s_and_b64 vcc, exec, s[0:1]
	s_cbranch_vccz .LBB0_3389
	v_mov_b32_e32 v16, v17
	v_cmp_le_u32_e64 s[38:39], s8, v238
	v_cmp_le_u32_e64 s[42:43], s8, v237
	v_cmp_le_u32_e64 s[62:63], s8, v236
	v_cmp_le_u32_e64 s[64:65], s8, v235
	v_cmp_le_u32_e64 s[66:67], s8, v234
	v_cmp_le_u32_e64 s[68:69], s8, v233
	v_cmp_le_u32_e64 s[70:71], s8, v231
	v_cmp_le_u32_e64 s[72:73], s8, v232
	v_addc_co_u32_e64 v16, s[38:39], 0, v16, s[38:39]
	v_addc_co_u32_e64 v16, s[42:43], 0, v16, s[42:43]
	v_addc_co_u32_e64 v16, s[62:63], 0, v16, s[62:63]
	v_addc_co_u32_e64 v16, s[64:65], 0, v16, s[64:65]
	v_addc_co_u32_e64 v16, s[66:67], 0, v16, s[66:67]
	v_addc_co_u32_e64 v16, s[68:69], 0, v16, s[68:69]
	v_addc_co_u32_e64 v16, s[70:71], 0, v16, s[70:71]
	v_addc_co_u32_e64 v16, s[72:73], 0, v16, s[72:73]
	v_cmp_le_u32_e64 s[38:39], s8, v230
	v_cmp_le_u32_e64 s[42:43], s8, v229
	v_cmp_le_u32_e64 s[62:63], s8, v228
	v_cmp_le_u32_e64 s[64:65], s8, v227
	v_cmp_le_u32_e64 s[66:67], s8, v226
	v_cmp_le_u32_e64 s[68:69], s8, v225
	v_cmp_le_u32_e64 s[70:71], s8, v223
	v_cmp_le_u32_e64 s[72:73], s8, v224
	v_addc_co_u32_e64 v16, s[38:39], 0, v16, s[38:39]
	v_addc_co_u32_e64 v16, s[42:43], 0, v16, s[42:43]
	v_addc_co_u32_e64 v16, s[62:63], 0, v16, s[62:63]
	v_addc_co_u32_e64 v16, s[64:65], 0, v16, s[64:65]
	v_addc_co_u32_e64 v16, s[66:67], 0, v16, s[66:67]
	v_addc_co_u32_e64 v16, s[68:69], 0, v16, s[68:69]
	v_addc_co_u32_e64 v16, s[70:71], 0, v16, s[70:71]
	v_addc_co_u32_e64 v16, s[72:73], 0, v16, s[72:73]
	v_cmp_le_u32_e64 s[38:39], s8, v222
	v_cmp_le_u32_e64 s[42:43], s8, v221
	v_cmp_le_u32_e64 s[62:63], s8, v220
	v_cmp_le_u32_e64 s[64:65], s8, v219
	v_cmp_le_u32_e64 s[66:67], s8, v218
	v_cmp_le_u32_e64 s[68:69], s8, v217
	v_cmp_le_u32_e64 s[70:71], s8, v215
	v_cmp_le_u32_e64 s[72:73], s8, v216
	v_addc_co_u32_e64 v16, s[38:39], 0, v16, s[38:39]
	v_addc_co_u32_e64 v16, s[42:43], 0, v16, s[42:43]
	v_addc_co_u32_e64 v16, s[62:63], 0, v16, s[62:63]
	v_addc_co_u32_e64 v16, s[64:65], 0, v16, s[64:65]
	v_addc_co_u32_e64 v16, s[66:67], 0, v16, s[66:67]
	v_addc_co_u32_e64 v16, s[68:69], 0, v16, s[68:69]
	v_addc_co_u32_e64 v16, s[70:71], 0, v16, s[70:71]
	v_addc_co_u32_e64 v16, s[72:73], 0, v16, s[72:73]
	v_cmp_le_u32_e64 s[38:39], s8, v214
	v_cmp_le_u32_e64 s[42:43], s8, v213
	v_cmp_le_u32_e64 s[62:63], s8, v212
	v_cmp_le_u32_e64 s[64:65], s8, v211
	v_cmp_le_u32_e64 s[66:67], s8, v210
	v_cmp_le_u32_e64 s[68:69], s8, v207
	v_cmp_le_u32_e64 s[70:71], s8, v194
	v_cmp_le_u32_e64 s[72:73], s8, v195
	v_addc_co_u32_e64 v16, s[38:39], 0, v16, s[38:39]
	v_addc_co_u32_e64 v16, s[42:43], 0, v16, s[42:43]
	v_addc_co_u32_e64 v16, s[62:63], 0, v16, s[62:63]
	v_addc_co_u32_e64 v16, s[64:65], 0, v16, s[64:65]
	v_addc_co_u32_e64 v16, s[66:67], 0, v16, s[66:67]
	v_addc_co_u32_e64 v16, s[68:69], 0, v16, s[68:69]
	v_addc_co_u32_e64 v16, s[70:71], 0, v16, s[70:71]
	v_addc_co_u32_e64 v16, s[72:73], 0, v16, s[72:73]
	v_cmp_le_u32_e64 s[38:39], s8, v193
	v_cmp_le_u32_e64 s[42:43], s8, v192
	v_cmp_le_u32_e64 s[62:63], s8, v191
	v_cmp_le_u32_e64 s[64:65], s8, v190
	v_cmp_le_u32_e64 s[66:67], s8, v189
	v_cmp_le_u32_e64 s[68:69], s8, v188
	v_cmp_le_u32_e64 s[70:71], s8, v186
	v_cmp_le_u32_e64 s[72:73], s8, v187
	v_addc_co_u32_e64 v16, s[38:39], 0, v16, s[38:39]
	v_addc_co_u32_e64 v16, s[42:43], 0, v16, s[42:43]
	v_addc_co_u32_e64 v16, s[62:63], 0, v16, s[62:63]
	v_addc_co_u32_e64 v16, s[64:65], 0, v16, s[64:65]
	v_addc_co_u32_e64 v16, s[66:67], 0, v16, s[66:67]
	v_addc_co_u32_e64 v16, s[68:69], 0, v16, s[68:69]
	v_addc_co_u32_e64 v16, s[70:71], 0, v16, s[70:71]
	v_addc_co_u32_e64 v16, s[72:73], 0, v16, s[72:73]
	v_cmp_le_u32_e64 s[38:39], s8, v185
	v_cmp_le_u32_e64 s[42:43], s8, v184
	v_cmp_le_u32_e64 s[62:63], s8, v183
	v_cmp_le_u32_e64 s[64:65], s8, v182
	v_cmp_le_u32_e64 s[66:67], s8, v181
	v_cmp_le_u32_e64 s[68:69], s8, v180
	v_cmp_le_u32_e64 s[70:71], s8, v178
	v_cmp_le_u32_e64 s[72:73], s8, v179
	v_addc_co_u32_e64 v16, s[38:39], 0, v16, s[38:39]
	v_addc_co_u32_e64 v16, s[42:43], 0, v16, s[42:43]
	v_addc_co_u32_e64 v16, s[62:63], 0, v16, s[62:63]
	v_addc_co_u32_e64 v16, s[64:65], 0, v16, s[64:65]
	v_addc_co_u32_e64 v16, s[66:67], 0, v16, s[66:67]
	v_addc_co_u32_e64 v16, s[68:69], 0, v16, s[68:69]
	v_addc_co_u32_e64 v16, s[70:71], 0, v16, s[70:71]
	v_addc_co_u32_e64 v16, s[72:73], 0, v16, s[72:73]
	v_cmp_le_u32_e64 s[38:39], s8, v177
	v_cmp_le_u32_e64 s[42:43], s8, v176
	v_cmp_le_u32_e64 s[62:63], s8, v175
	v_cmp_le_u32_e64 s[64:65], s8, v174
	v_cmp_le_u32_e64 s[66:67], s8, v173
	v_cmp_le_u32_e64 s[68:69], s8, v172
	v_cmp_le_u32_e64 s[70:71], s8, v115
	v_cmp_le_u32_e64 s[72:73], s8, v243
	v_addc_co_u32_e64 v16, s[38:39], 0, v16, s[38:39]
	v_addc_co_u32_e64 v16, s[42:43], 0, v16, s[42:43]
	v_addc_co_u32_e64 v16, s[62:63], 0, v16, s[62:63]
	v_addc_co_u32_e64 v16, s[64:65], 0, v16, s[64:65]
	v_addc_co_u32_e64 v16, s[66:67], 0, v16, s[66:67]
	v_addc_co_u32_e64 v16, s[68:69], 0, v16, s[68:69]
	v_addc_co_u32_e64 v16, s[70:71], 0, v16, s[70:71]
	v_addc_co_u32_e64 v16, s[72:73], 0, v16, s[72:73]
	v_cmp_le_u32_e64 s[38:39], s8, v242
	v_cmp_le_u32_e64 s[42:43], s8, v241
	v_cmp_le_u32_e64 s[62:63], s8, v240
	v_cmp_le_u32_e64 s[64:65], s8, v171
	v_cmp_le_u32_e64 s[66:67], s8, v170
	v_cmp_le_u32_e64 s[68:69], s8, v169
	v_cmp_le_u32_e64 s[70:71], s8, v168
	v_addc_co_u32_e64 v16, s[38:39], 0, v16, s[38:39]
	v_addc_co_u32_e64 v16, s[42:43], 0, v16, s[42:43]
	v_addc_co_u32_e64 v16, s[62:63], 0, v16, s[62:63]
	v_addc_co_u32_e64 v16, s[64:65], 0, v16, s[64:65]
	v_addc_co_u32_e64 v16, s[66:67], 0, v16, s[66:67]
	v_addc_co_u32_e64 v16, s[68:69], 0, v16, s[68:69]
	v_addc_co_u32_e64 v16, s[70:71], 0, v16, s[70:71]
	v_cmp_le_u32_e32 vcc, s8, v239
	v_add_u32_e32 v167, -1, v252
	s_nop 0
	v_addc_co_u32_e64 v16, s[0:1], 0, v16, vcc
	v_add_u32_e32 v239, -2, v252
	v_mov_b32_e32 v167, v16
	s_nop 1
	v_add_u32_dpp v167, v167, v167 row_shr:1 row_mask:0xf bank_mask:0xf bound_ctrl:1
	s_nop 1
	v_add_u32_dpp v167, v167, v167 row_shr:2 row_mask:0xf bank_mask:0xf bound_ctrl:1
	s_nop 1
	v_add_u32_dpp v167, v167, v167 row_shr:4 row_mask:0xf bank_mask:0xf bound_ctrl:1
	s_nop 1
	v_add_u32_dpp v167, v167, v167 row_shr:8 row_mask:0xf bank_mask:0xf bound_ctrl:1
	s_nop 1
	v_add_u32_dpp v167, v167, v167 row_bcast:15 row_mask:0xa bank_mask:0xf
	s_nop 1
	v_add_u32_dpp v167, v167, v167 row_bcast:31 row_mask:0xc bank_mask:0xf
	s_nop 0
	v_sub_u32_e32 v166, v167, v16
	s_and_saveexec_b64 s[0:1], vcc
	s_cbranch_execz .LBB0_3264
	v_add_u32_e32 v16, 1, v166
	v_lshl_add_u32 v167, v166, 1, s100
	ds_write_b16 v167, v114
	v_mov_b32_e32 v166, v16
	s_or_b64 exec, exec, s[0:1]
	v_cmp_le_u32_e32 vcc, s8, v238
	s_and_saveexec_b64 s[0:1], vcc
	s_cbranch_execnz .LBB0_3265
